# elem prologue (GDN layers): a/b weight column loads to LDS issued 16 at a time instead of 4-per-wait loop
# speedup vs baseline: 1.0041x; 1.0001x over previous
.LBB0_48:
	s_mov_b64 s[8:9], s[94:95]
	s_lshr_b32 s6, s76, 1
	v_writelane_b32 v251, s6, 3
	s_load_dwordx4 s[44:47], s[8:9], 0x0
	s_load_dwordx4 s[52:55], s[8:9], 0x40
	s_load_dwordx4 s[48:51], s[8:9], 0xc8
	v_writelane_b32 v251, s7, 4
	s_and_b32 s6, s76, 1
	s_cmp_eq_u32 s6, 0
	s_cselect_b64 s[64:65], -1, 0
	s_cmp_eq_u32 s6, 1
	v_mov_b32_e32 v0, v214
	s_cselect_b64 s[90:91], -1, 0
	s_and_b64 vcc, exec, s[90:91]
	v_readfirstlane_b32 s14, v0
	s_cbranch_vccnz .LBB0_62
	s_movk_i32 s6, 0x4000
	v_cmp_gt_i32_e32 vcc, s6, v0
	s_and_saveexec_b64 s[6:7], vcc
	s_cbranch_execz .LBB0_61
	s_load_dwordx2 s[8:9], s[8:9], 0x60
	v_readlane_b32 s10, v251, 3
	s_mul_i32 s10, s10, 0x1010000
	v_and_b32_e32 v1, 15, v0
	v_lshlrev_b32_e32 v172, 2, v1
	s_waitcnt lgkmcnt(0)
	s_add_u32 s8, s8, s10
	v_lshl_add_u32 v6, v1, 12, 0
	s_addc_u32 s9, s9, 0
	v_max_i32_e32 v1, 0x3e00, v0
	v_lshl_add_u64 v[2:3], s[8:9], 0, v[172:173]
	s_mov_b64 s[8:9], 0x4000
	v_sub_u32_e32 v1, v1, v0
	v_readlane_b32 s11, v251, 4
	v_lshl_add_u64 v[2:3], v[2:3], 0, s[8:9]
	v_ashrrev_i32_e32 v1, 4, v0
	v_mad_i64_i32 v[4:5], s[10:11], v1, s87, v[2:3]
	v_lshl_add_u32 v1, v1, 2, v6
	s_mov_b32 s10, 0x80800
	s_mov_b32 s11, 0
	global_load_dword v2, v[4:5], off
	v_lshl_add_u64 v[4:5], v[4:5], 0, s[10:11]
	global_load_dword v3, v[4:5], off
	v_lshl_add_u64 v[4:5], v[4:5], 0, s[10:11]
	global_load_dword v6, v[4:5], off
	v_lshl_add_u64 v[4:5], v[4:5], 0, s[10:11]
	global_load_dword v7, v[4:5], off
	v_lshl_add_u64 v[4:5], v[4:5], 0, s[10:11]
	global_load_dword v8, v[4:5], off
	v_lshl_add_u64 v[4:5], v[4:5], 0, s[10:11]
	global_load_dword v9, v[4:5], off
	v_lshl_add_u64 v[4:5], v[4:5], 0, s[10:11]
	global_load_dword v10, v[4:5], off
	v_lshl_add_u64 v[4:5], v[4:5], 0, s[10:11]
	global_load_dword v11, v[4:5], off
	v_lshl_add_u64 v[4:5], v[4:5], 0, s[10:11]
	global_load_dword v12, v[4:5], off
	v_lshl_add_u64 v[4:5], v[4:5], 0, s[10:11]
	global_load_dword v13, v[4:5], off
	v_lshl_add_u64 v[4:5], v[4:5], 0, s[10:11]
	global_load_dword v14, v[4:5], off
	v_lshl_add_u64 v[4:5], v[4:5], 0, s[10:11]
	global_load_dword v15, v[4:5], off
	v_lshl_add_u64 v[4:5], v[4:5], 0, s[10:11]
	global_load_dword v16, v[4:5], off
	v_lshl_add_u64 v[4:5], v[4:5], 0, s[10:11]
	global_load_dword v17, v[4:5], off
	v_lshl_add_u64 v[4:5], v[4:5], 0, s[10:11]
	global_load_dword v18, v[4:5], off
	v_lshl_add_u64 v[4:5], v[4:5], 0, s[10:11]
	global_load_dword v19, v[4:5], off
	v_lshl_add_u64 v[4:5], v[4:5], 0, s[10:11]
	s_waitcnt vmcnt(15)
	ds_write_b32 v1, v2
	s_waitcnt vmcnt(14)
	ds_write_b32 v1, v3 offset:128
	s_waitcnt vmcnt(13)
	ds_write_b32 v1, v6 offset:256
	s_waitcnt vmcnt(12)
	ds_write_b32 v1, v7 offset:384
	s_waitcnt vmcnt(11)
	ds_write_b32 v1, v8 offset:512
	s_waitcnt vmcnt(10)
	ds_write_b32 v1, v9 offset:640
	s_waitcnt vmcnt(9)
	ds_write_b32 v1, v10 offset:768
	s_waitcnt vmcnt(8)
	ds_write_b32 v1, v11 offset:896
	s_waitcnt vmcnt(7)
	ds_write_b32 v1, v12 offset:1024
	s_waitcnt vmcnt(6)
	ds_write_b32 v1, v13 offset:1152
	s_waitcnt vmcnt(5)
	ds_write_b32 v1, v14 offset:1280
	s_waitcnt vmcnt(4)
	ds_write_b32 v1, v15 offset:1408
	s_waitcnt vmcnt(3)
	ds_write_b32 v1, v16 offset:1536
	s_waitcnt vmcnt(2)
	ds_write_b32 v1, v17 offset:1664
	s_waitcnt vmcnt(1)
	ds_write_b32 v1, v18 offset:1792
	s_waitcnt vmcnt(0)
	ds_write_b32 v1, v19 offset:1920
	s_waitcnt lgkmcnt(0)
	global_load_dword v2, v[4:5], off
	v_lshl_add_u64 v[4:5], v[4:5], 0, s[10:11]
	global_load_dword v3, v[4:5], off
	v_lshl_add_u64 v[4:5], v[4:5], 0, s[10:11]
	global_load_dword v6, v[4:5], off
	v_lshl_add_u64 v[4:5], v[4:5], 0, s[10:11]
	global_load_dword v7, v[4:5], off
	v_lshl_add_u64 v[4:5], v[4:5], 0, s[10:11]
	global_load_dword v8, v[4:5], off
	v_lshl_add_u64 v[4:5], v[4:5], 0, s[10:11]
	global_load_dword v9, v[4:5], off
	v_lshl_add_u64 v[4:5], v[4:5], 0, s[10:11]
	global_load_dword v10, v[4:5], off
	v_lshl_add_u64 v[4:5], v[4:5], 0, s[10:11]
	global_load_dword v11, v[4:5], off
	v_lshl_add_u64 v[4:5], v[4:5], 0, s[10:11]
	global_load_dword v12, v[4:5], off
	v_lshl_add_u64 v[4:5], v[4:5], 0, s[10:11]
	global_load_dword v13, v[4:5], off
	v_lshl_add_u64 v[4:5], v[4:5], 0, s[10:11]
	global_load_dword v14, v[4:5], off
	v_lshl_add_u64 v[4:5], v[4:5], 0, s[10:11]
	global_load_dword v15, v[4:5], off
	v_lshl_add_u64 v[4:5], v[4:5], 0, s[10:11]
	global_load_dword v16, v[4:5], off
	v_lshl_add_u64 v[4:5], v[4:5], 0, s[10:11]
	global_load_dword v17, v[4:5], off
	v_lshl_add_u64 v[4:5], v[4:5], 0, s[10:11]
	global_load_dword v18, v[4:5], off
	v_lshl_add_u64 v[4:5], v[4:5], 0, s[10:11]
	global_load_dword v19, v[4:5], off
	v_lshl_add_u64 v[4:5], v[4:5], 0, s[10:11]
	s_waitcnt vmcnt(15)
	ds_write_b32 v1, v2 offset:2048
	s_waitcnt vmcnt(14)
	ds_write_b32 v1, v3 offset:2176
	s_waitcnt vmcnt(13)
	ds_write_b32 v1, v6 offset:2304
	s_waitcnt vmcnt(12)
	ds_write_b32 v1, v7 offset:2432
	s_waitcnt vmcnt(11)
	ds_write_b32 v1, v8 offset:2560
	s_waitcnt vmcnt(10)
	ds_write_b32 v1, v9 offset:2688
	s_waitcnt vmcnt(9)
	ds_write_b32 v1, v10 offset:2816
	s_waitcnt vmcnt(8)
	ds_write_b32 v1, v11 offset:2944
	s_waitcnt vmcnt(7)
	ds_write_b32 v1, v12 offset:3072
	s_waitcnt vmcnt(6)
	ds_write_b32 v1, v13 offset:3200
	s_waitcnt vmcnt(5)
	ds_write_b32 v1, v14 offset:3328
	s_waitcnt vmcnt(4)
	ds_write_b32 v1, v15 offset:3456
	s_waitcnt vmcnt(3)
	ds_write_b32 v1, v16 offset:3584
	s_waitcnt vmcnt(2)
	ds_write_b32 v1, v17 offset:3712
	s_waitcnt vmcnt(1)
	ds_write_b32 v1, v18 offset:3840
	s_waitcnt vmcnt(0)
	ds_write_b32 v1, v19 offset:3968
